# scan consumer loop hand-scheduled: 16-step unroll, two operand register sets (no rotation moves), DPP wait states filled with independent work, no s_setprio raise
# speedup vs baseline: 1.0333x; 1.0333x over previous
.LBB0_1052:
	s_and_saveexec_b64 s[6:7], vcc
	s_xor_b64 s[6:7], exec, s[6:7]
	s_cbranch_execz .LBB0_1062
	s_waitcnt lgkmcnt(0)
	s_barrier
	s_setprio 0
	v_mov_b32_e32 v134, v135
	s_waitcnt vmcnt(0)
	v_mov_b32_e32 v20, 0
	v_mov_b32_e32 v21, 0
	v_mov_b32_e32 v22, 0
	v_mov_b32_e32 v23, 0
	v_add_u32_e32 v253, v55, v59
	v_lshl_add_u32 v254, v51, 2, v55
	s_mov_b32 s52, 0
.Lsc_chunk:
	s_and_b32 s54, s52, 1
	s_mul_i32 s55, s54, 0xa400
	s_lshl_b32 s54, s54, 14
	v_add_u32_e32 v17, s55, v253
	v_add_u32_e32 v19, s55, v254
	v_add_u32_e32 v252, s54, v57
	ds_read_b128 v[0:3], v17 offset:4096
	ds_read_b128 v[4:7], v17 offset:12288
	ds_read_b32 v16, v19 offset:20480
	ds_read_b128 v[8:11], v17
	ds_read_b128 v[12:15], v17 offset:8192
	s_waitcnt lgkmcnt(4)
	v_pk_mul_f32 v[76:77], v[20:21], v[0:1]
	ds_read_b128 v[24:27], v17 offset:4352
	v_pk_fma_f32 v[76:77], v[22:23], v[2:3], v[76:77]
	ds_read_b128 v[28:31], v17 offset:12544
	v_add_f32_e32 v76, v76, v77
	ds_read_b32 v18, v19 offset:20512
	ds_read_b128 v[32:35], v17 offset:256
	v_add_f32_dpp v76, v76, v76 quad_perm:[1,0,3,2] row_mask:0xf bank_mask:0xf bound_ctrl:1
	s_waitcnt lgkmcnt(6)
	v_pk_mul_f32 v[78:79], v[4:5], v[16:17] op_sel_hi:[1,0]
	v_pk_mul_f32 v[80:81], v[6:7], v[16:17] op_sel_hi:[1,0]
	v_add_f32_dpp v76, v76, v76 quad_perm:[2,3,0,1] row_mask:0xf bank_mask:0xf bound_ctrl:1
	s_waitcnt lgkmcnt(5)
	v_pk_fma_f32 v[78:79], v[20:21], v[8:9], v[78:79]
	v_add_f32_dpp v76, v76, v76 row_half_mirror row_mask:0xf bank_mask:0xf bound_ctrl:1
	v_pk_fma_f32 v[80:81], v[22:23], v[10:11], v[80:81]
	s_nop 0
	v_add_f32_dpp v76, v76, v76 row_ror:8 row_mask:0xf bank_mask:0xf bound_ctrl:1
	ds_read_b128 v[68:71], v17 offset:16384
	s_waitcnt lgkmcnt(5)
	v_pk_fma_f32 v[20:21], v[12:13], v[76:77], v[78:79] op_sel_hi:[1,0,1] neg_lo:[1,0,0] neg_hi:[1,0,0]
	v_pk_fma_f32 v[22:23], v[14:15], v[76:77], v[80:81] op_sel_hi:[1,0,1] neg_lo:[1,0,0] neg_hi:[1,0,0]
	ds_read_b128 v[36:39], v17 offset:8448
	s_waitcnt lgkmcnt(5)
	v_pk_mul_f32 v[76:77], v[20:21], v[24:25]
	ds_read_b128 v[0:3], v17 offset:4608
	v_pk_fma_f32 v[76:77], v[22:23], v[26:27], v[76:77]
	ds_read_b128 v[4:7], v17 offset:12800
	v_add_f32_e32 v76, v76, v77
	ds_read_b32 v16, v19 offset:20544
	ds_read_b128 v[8:11], v17 offset:512
	v_add_f32_dpp v76, v76, v76 quad_perm:[1,0,3,2] row_mask:0xf bank_mask:0xf bound_ctrl:1
	s_waitcnt lgkmcnt(7)
	v_pk_mul_f32 v[78:79], v[28:29], v[18:19] op_sel_hi:[1,0]
	v_pk_mul_f32 v[80:81], v[30:31], v[18:19] op_sel_hi:[1,0]
	v_add_f32_dpp v76, v76, v76 quad_perm:[2,3,0,1] row_mask:0xf bank_mask:0xf bound_ctrl:1
	s_waitcnt lgkmcnt(5)
	v_pk_mul_f32 v[250:251], v[68:69], v[20:21]
	v_pk_fma_f32 v[78:79], v[20:21], v[32:33], v[78:79]
	v_add_f32_dpp v76, v76, v76 row_half_mirror row_mask:0xf bank_mask:0xf bound_ctrl:1
	v_pk_fma_f32 v[250:251], v[70:71], v[22:23], v[250:251]
	v_pk_fma_f32 v[80:81], v[22:23], v[34:35], v[80:81]
	v_add_f32_dpp v76, v76, v76 row_ror:8 row_mask:0xf bank_mask:0xf bound_ctrl:1
	ds_read_b128 v[72:75], v17 offset:16640
	s_waitcnt lgkmcnt(5)
	v_pk_fma_f32 v[20:21], v[36:37], v[76:77], v[78:79] op_sel_hi:[1,0,1] neg_lo:[1,0,0] neg_hi:[1,0,0]
	v_pk_fma_f32 v[22:23], v[38:39], v[76:77], v[80:81] op_sel_hi:[1,0,1] neg_lo:[1,0,0] neg_hi:[1,0,0]
	v_add_f32_e32 v250, v250, v251
	ds_read_b128 v[12:15], v17 offset:8704
	ds_write_b32 v252, v250 offset:0
	s_waitcnt lgkmcnt(6)
	v_pk_mul_f32 v[76:77], v[20:21], v[0:1]
	ds_read_b128 v[24:27], v17 offset:4864
	v_pk_fma_f32 v[76:77], v[22:23], v[2:3], v[76:77]
	ds_read_b128 v[28:31], v17 offset:13056
	v_add_f32_e32 v76, v76, v77
	ds_read_b32 v18, v19 offset:20576
	ds_read_b128 v[32:35], v17 offset:768
	v_add_f32_dpp v76, v76, v76 quad_perm:[1,0,3,2] row_mask:0xf bank_mask:0xf bound_ctrl:1
	s_waitcnt lgkmcnt(8)
	v_pk_mul_f32 v[78:79], v[4:5], v[16:17] op_sel_hi:[1,0]
	v_pk_mul_f32 v[80:81], v[6:7], v[16:17] op_sel_hi:[1,0]
	v_add_f32_dpp v76, v76, v76 quad_perm:[2,3,0,1] row_mask:0xf bank_mask:0xf bound_ctrl:1
	s_waitcnt lgkmcnt(6)
	v_pk_mul_f32 v[250:251], v[72:73], v[20:21]
	v_pk_fma_f32 v[78:79], v[20:21], v[8:9], v[78:79]
	v_add_f32_dpp v76, v76, v76 row_half_mirror row_mask:0xf bank_mask:0xf bound_ctrl:1
	v_pk_fma_f32 v[250:251], v[74:75], v[22:23], v[250:251]
	v_pk_fma_f32 v[80:81], v[22:23], v[10:11], v[80:81]
	v_add_f32_dpp v76, v76, v76 row_ror:8 row_mask:0xf bank_mask:0xf bound_ctrl:1
	ds_read_b128 v[68:71], v17 offset:16896
	s_waitcnt lgkmcnt(6)
	v_pk_fma_f32 v[20:21], v[12:13], v[76:77], v[78:79] op_sel_hi:[1,0,1] neg_lo:[1,0,0] neg_hi:[1,0,0]
	v_pk_fma_f32 v[22:23], v[14:15], v[76:77], v[80:81] op_sel_hi:[1,0,1] neg_lo:[1,0,0] neg_hi:[1,0,0]
	v_add_f32_e32 v250, v250, v251
	ds_read_b128 v[36:39], v17 offset:8960
	ds_write_b32 v252, v250 offset:512
	s_waitcnt lgkmcnt(6)
	v_pk_mul_f32 v[76:77], v[20:21], v[24:25]
	ds_read_b128 v[0:3], v17 offset:5120
	v_pk_fma_f32 v[76:77], v[22:23], v[26:27], v[76:77]
	ds_read_b128 v[4:7], v17 offset:13312
	v_add_f32_e32 v76, v76, v77
	ds_read_b32 v16, v19 offset:20608
	ds_read_b128 v[8:11], v17 offset:1024
	v_add_f32_dpp v76, v76, v76 quad_perm:[1,0,3,2] row_mask:0xf bank_mask:0xf bound_ctrl:1
	s_waitcnt lgkmcnt(8)
	v_pk_mul_f32 v[78:79], v[28:29], v[18:19] op_sel_hi:[1,0]
	v_pk_mul_f32 v[80:81], v[30:31], v[18:19] op_sel_hi:[1,0]
	v_add_f32_dpp v76, v76, v76 quad_perm:[2,3,0,1] row_mask:0xf bank_mask:0xf bound_ctrl:1
	s_waitcnt lgkmcnt(6)
	v_pk_mul_f32 v[250:251], v[68:69], v[20:21]
	v_pk_fma_f32 v[78:79], v[20:21], v[32:33], v[78:79]
	v_add_f32_dpp v76, v76, v76 row_half_mirror row_mask:0xf bank_mask:0xf bound_ctrl:1
	v_pk_fma_f32 v[250:251], v[70:71], v[22:23], v[250:251]
	v_pk_fma_f32 v[80:81], v[22:23], v[34:35], v[80:81]
	v_add_f32_dpp v76, v76, v76 row_ror:8 row_mask:0xf bank_mask:0xf bound_ctrl:1
	ds_read_b128 v[72:75], v17 offset:17152
	s_waitcnt lgkmcnt(6)
	v_pk_fma_f32 v[20:21], v[36:37], v[76:77], v[78:79] op_sel_hi:[1,0,1] neg_lo:[1,0,0] neg_hi:[1,0,0]
	v_pk_fma_f32 v[22:23], v[38:39], v[76:77], v[80:81] op_sel_hi:[1,0,1] neg_lo:[1,0,0] neg_hi:[1,0,0]
	v_add_f32_e32 v250, v250, v251
	ds_read_b128 v[12:15], v17 offset:9216
	ds_write_b32 v252, v250 offset:1024
	s_waitcnt lgkmcnt(6)
	v_pk_mul_f32 v[76:77], v[20:21], v[0:1]
	ds_read_b128 v[24:27], v17 offset:5376
	v_pk_fma_f32 v[76:77], v[22:23], v[2:3], v[76:77]
	ds_read_b128 v[28:31], v17 offset:13568
	v_add_f32_e32 v76, v76, v77
	ds_read_b32 v18, v19 offset:20640
	ds_read_b128 v[32:35], v17 offset:1280
	v_add_f32_dpp v76, v76, v76 quad_perm:[1,0,3,2] row_mask:0xf bank_mask:0xf bound_ctrl:1
	s_waitcnt lgkmcnt(8)
	v_pk_mul_f32 v[78:79], v[4:5], v[16:17] op_sel_hi:[1,0]
	v_pk_mul_f32 v[80:81], v[6:7], v[16:17] op_sel_hi:[1,0]
	v_add_f32_dpp v76, v76, v76 quad_perm:[2,3,0,1] row_mask:0xf bank_mask:0xf bound_ctrl:1
	s_waitcnt lgkmcnt(6)
	v_pk_mul_f32 v[250:251], v[72:73], v[20:21]
	v_pk_fma_f32 v[78:79], v[20:21], v[8:9], v[78:79]
	v_add_f32_dpp v76, v76, v76 row_half_mirror row_mask:0xf bank_mask:0xf bound_ctrl:1
	v_pk_fma_f32 v[250:251], v[74:75], v[22:23], v[250:251]
	v_pk_fma_f32 v[80:81], v[22:23], v[10:11], v[80:81]
	v_add_f32_dpp v76, v76, v76 row_ror:8 row_mask:0xf bank_mask:0xf bound_ctrl:1
	ds_read_b128 v[68:71], v17 offset:17408
	s_waitcnt lgkmcnt(6)
	v_pk_fma_f32 v[20:21], v[12:13], v[76:77], v[78:79] op_sel_hi:[1,0,1] neg_lo:[1,0,0] neg_hi:[1,0,0]
	v_pk_fma_f32 v[22:23], v[14:15], v[76:77], v[80:81] op_sel_hi:[1,0,1] neg_lo:[1,0,0] neg_hi:[1,0,0]
	v_add_f32_e32 v250, v250, v251
	ds_read_b128 v[36:39], v17 offset:9472
	ds_write_b32 v252, v250 offset:1536
	s_waitcnt lgkmcnt(6)
	v_pk_mul_f32 v[76:77], v[20:21], v[24:25]
	ds_read_b128 v[0:3], v17 offset:5632
	v_pk_fma_f32 v[76:77], v[22:23], v[26:27], v[76:77]
	ds_read_b128 v[4:7], v17 offset:13824
	v_add_f32_e32 v76, v76, v77
	ds_read_b32 v16, v19 offset:20672
	ds_read_b128 v[8:11], v17 offset:1536
	v_add_f32_dpp v76, v76, v76 quad_perm:[1,0,3,2] row_mask:0xf bank_mask:0xf bound_ctrl:1
	s_waitcnt lgkmcnt(8)
	v_pk_mul_f32 v[78:79], v[28:29], v[18:19] op_sel_hi:[1,0]
	v_pk_mul_f32 v[80:81], v[30:31], v[18:19] op_sel_hi:[1,0]
	v_add_f32_dpp v76, v76, v76 quad_perm:[2,3,0,1] row_mask:0xf bank_mask:0xf bound_ctrl:1
	s_waitcnt lgkmcnt(6)
	v_pk_mul_f32 v[250:251], v[68:69], v[20:21]
	v_pk_fma_f32 v[78:79], v[20:21], v[32:33], v[78:79]
	v_add_f32_dpp v76, v76, v76 row_half_mirror row_mask:0xf bank_mask:0xf bound_ctrl:1
	v_pk_fma_f32 v[250:251], v[70:71], v[22:23], v[250:251]
	v_pk_fma_f32 v[80:81], v[22:23], v[34:35], v[80:81]
	v_add_f32_dpp v76, v76, v76 row_ror:8 row_mask:0xf bank_mask:0xf bound_ctrl:1
	ds_read_b128 v[72:75], v17 offset:17664
	s_waitcnt lgkmcnt(6)
	v_pk_fma_f32 v[20:21], v[36:37], v[76:77], v[78:79] op_sel_hi:[1,0,1] neg_lo:[1,0,0] neg_hi:[1,0,0]
	v_pk_fma_f32 v[22:23], v[38:39], v[76:77], v[80:81] op_sel_hi:[1,0,1] neg_lo:[1,0,0] neg_hi:[1,0,0]
	v_add_f32_e32 v250, v250, v251
	ds_read_b128 v[12:15], v17 offset:9728
	ds_write_b32 v252, v250 offset:2048
	s_waitcnt lgkmcnt(6)
	v_pk_mul_f32 v[76:77], v[20:21], v[0:1]
	ds_read_b128 v[24:27], v17 offset:5888
	v_pk_fma_f32 v[76:77], v[22:23], v[2:3], v[76:77]
	ds_read_b128 v[28:31], v17 offset:14080
	v_add_f32_e32 v76, v76, v77
	ds_read_b32 v18, v19 offset:20704
	ds_read_b128 v[32:35], v17 offset:1792
	v_add_f32_dpp v76, v76, v76 quad_perm:[1,0,3,2] row_mask:0xf bank_mask:0xf bound_ctrl:1
	s_waitcnt lgkmcnt(8)
	v_pk_mul_f32 v[78:79], v[4:5], v[16:17] op_sel_hi:[1,0]
	v_pk_mul_f32 v[80:81], v[6:7], v[16:17] op_sel_hi:[1,0]
	v_add_f32_dpp v76, v76, v76 quad_perm:[2,3,0,1] row_mask:0xf bank_mask:0xf bound_ctrl:1
	s_waitcnt lgkmcnt(6)
	v_pk_mul_f32 v[250:251], v[72:73], v[20:21]
	v_pk_fma_f32 v[78:79], v[20:21], v[8:9], v[78:79]
	v_add_f32_dpp v76, v76, v76 row_half_mirror row_mask:0xf bank_mask:0xf bound_ctrl:1
	v_pk_fma_f32 v[250:251], v[74:75], v[22:23], v[250:251]
	v_pk_fma_f32 v[80:81], v[22:23], v[10:11], v[80:81]
	v_add_f32_dpp v76, v76, v76 row_ror:8 row_mask:0xf bank_mask:0xf bound_ctrl:1
	ds_read_b128 v[68:71], v17 offset:17920
	s_waitcnt lgkmcnt(6)
	v_pk_fma_f32 v[20:21], v[12:13], v[76:77], v[78:79] op_sel_hi:[1,0,1] neg_lo:[1,0,0] neg_hi:[1,0,0]
	v_pk_fma_f32 v[22:23], v[14:15], v[76:77], v[80:81] op_sel_hi:[1,0,1] neg_lo:[1,0,0] neg_hi:[1,0,0]
	v_add_f32_e32 v250, v250, v251
	ds_read_b128 v[36:39], v17 offset:9984
	ds_write_b32 v252, v250 offset:2560
	s_waitcnt lgkmcnt(6)
	v_pk_mul_f32 v[76:77], v[20:21], v[24:25]
	ds_read_b128 v[0:3], v17 offset:6144
	v_pk_fma_f32 v[76:77], v[22:23], v[26:27], v[76:77]
	ds_read_b128 v[4:7], v17 offset:14336
	v_add_f32_e32 v76, v76, v77
	ds_read_b32 v16, v19 offset:20736
	ds_read_b128 v[8:11], v17 offset:2048
	v_add_f32_dpp v76, v76, v76 quad_perm:[1,0,3,2] row_mask:0xf bank_mask:0xf bound_ctrl:1
	s_waitcnt lgkmcnt(8)
	v_pk_mul_f32 v[78:79], v[28:29], v[18:19] op_sel_hi:[1,0]
	v_pk_mul_f32 v[80:81], v[30:31], v[18:19] op_sel_hi:[1,0]
	v_add_f32_dpp v76, v76, v76 quad_perm:[2,3,0,1] row_mask:0xf bank_mask:0xf bound_ctrl:1
	s_waitcnt lgkmcnt(6)
	v_pk_mul_f32 v[250:251], v[68:69], v[20:21]
	v_pk_fma_f32 v[78:79], v[20:21], v[32:33], v[78:79]
	v_add_f32_dpp v76, v76, v76 row_half_mirror row_mask:0xf bank_mask:0xf bound_ctrl:1
	v_pk_fma_f32 v[250:251], v[70:71], v[22:23], v[250:251]
	v_pk_fma_f32 v[80:81], v[22:23], v[34:35], v[80:81]
	v_add_f32_dpp v76, v76, v76 row_ror:8 row_mask:0xf bank_mask:0xf bound_ctrl:1
	ds_read_b128 v[72:75], v17 offset:18176
	s_waitcnt lgkmcnt(6)
	v_pk_fma_f32 v[20:21], v[36:37], v[76:77], v[78:79] op_sel_hi:[1,0,1] neg_lo:[1,0,0] neg_hi:[1,0,0]
	v_pk_fma_f32 v[22:23], v[38:39], v[76:77], v[80:81] op_sel_hi:[1,0,1] neg_lo:[1,0,0] neg_hi:[1,0,0]
	v_add_f32_e32 v250, v250, v251
	ds_read_b128 v[12:15], v17 offset:10240
	ds_write_b32 v252, v250 offset:3072
	s_waitcnt lgkmcnt(6)
	v_pk_mul_f32 v[76:77], v[20:21], v[0:1]
	ds_read_b128 v[24:27], v17 offset:6400
	v_pk_fma_f32 v[76:77], v[22:23], v[2:3], v[76:77]
	ds_read_b128 v[28:31], v17 offset:14592
	v_add_f32_e32 v76, v76, v77
	ds_read_b32 v18, v19 offset:20768
	ds_read_b128 v[32:35], v17 offset:2304
	v_add_f32_dpp v76, v76, v76 quad_perm:[1,0,3,2] row_mask:0xf bank_mask:0xf bound_ctrl:1
	s_waitcnt lgkmcnt(8)
	v_pk_mul_f32 v[78:79], v[4:5], v[16:17] op_sel_hi:[1,0]
	v_pk_mul_f32 v[80:81], v[6:7], v[16:17] op_sel_hi:[1,0]
	v_add_f32_dpp v76, v76, v76 quad_perm:[2,3,0,1] row_mask:0xf bank_mask:0xf bound_ctrl:1
	s_waitcnt lgkmcnt(6)
	v_pk_mul_f32 v[250:251], v[72:73], v[20:21]
	v_pk_fma_f32 v[78:79], v[20:21], v[8:9], v[78:79]
	v_add_f32_dpp v76, v76, v76 row_half_mirror row_mask:0xf bank_mask:0xf bound_ctrl:1
	v_pk_fma_f32 v[250:251], v[74:75], v[22:23], v[250:251]
	v_pk_fma_f32 v[80:81], v[22:23], v[10:11], v[80:81]
	v_add_f32_dpp v76, v76, v76 row_ror:8 row_mask:0xf bank_mask:0xf bound_ctrl:1
	ds_read_b128 v[68:71], v17 offset:18432
	s_waitcnt lgkmcnt(6)
	v_pk_fma_f32 v[20:21], v[12:13], v[76:77], v[78:79] op_sel_hi:[1,0,1] neg_lo:[1,0,0] neg_hi:[1,0,0]
	v_pk_fma_f32 v[22:23], v[14:15], v[76:77], v[80:81] op_sel_hi:[1,0,1] neg_lo:[1,0,0] neg_hi:[1,0,0]
	v_add_f32_e32 v250, v250, v251
	ds_read_b128 v[36:39], v17 offset:10496
	ds_write_b32 v252, v250 offset:3584
	s_waitcnt lgkmcnt(6)
	v_pk_mul_f32 v[76:77], v[20:21], v[24:25]
	ds_read_b128 v[0:3], v17 offset:6656
	v_pk_fma_f32 v[76:77], v[22:23], v[26:27], v[76:77]
	ds_read_b128 v[4:7], v17 offset:14848
	v_add_f32_e32 v76, v76, v77
	ds_read_b32 v16, v19 offset:20800
	ds_read_b128 v[8:11], v17 offset:2560
	v_add_f32_dpp v76, v76, v76 quad_perm:[1,0,3,2] row_mask:0xf bank_mask:0xf bound_ctrl:1
	s_waitcnt lgkmcnt(8)
	v_pk_mul_f32 v[78:79], v[28:29], v[18:19] op_sel_hi:[1,0]
	v_pk_mul_f32 v[80:81], v[30:31], v[18:19] op_sel_hi:[1,0]
	v_add_f32_dpp v76, v76, v76 quad_perm:[2,3,0,1] row_mask:0xf bank_mask:0xf bound_ctrl:1
	s_waitcnt lgkmcnt(6)
	v_pk_mul_f32 v[250:251], v[68:69], v[20:21]
	v_pk_fma_f32 v[78:79], v[20:21], v[32:33], v[78:79]
	v_add_f32_dpp v76, v76, v76 row_half_mirror row_mask:0xf bank_mask:0xf bound_ctrl:1
	v_pk_fma_f32 v[250:251], v[70:71], v[22:23], v[250:251]
	v_pk_fma_f32 v[80:81], v[22:23], v[34:35], v[80:81]
	v_add_f32_dpp v76, v76, v76 row_ror:8 row_mask:0xf bank_mask:0xf bound_ctrl:1
	ds_read_b128 v[72:75], v17 offset:18688
	s_waitcnt lgkmcnt(6)
	v_pk_fma_f32 v[20:21], v[36:37], v[76:77], v[78:79] op_sel_hi:[1,0,1] neg_lo:[1,0,0] neg_hi:[1,0,0]
	v_pk_fma_f32 v[22:23], v[38:39], v[76:77], v[80:81] op_sel_hi:[1,0,1] neg_lo:[1,0,0] neg_hi:[1,0,0]
	v_add_f32_e32 v250, v250, v251
	ds_read_b128 v[12:15], v17 offset:10752
	ds_write_b32 v252, v250 offset:4096
	s_waitcnt lgkmcnt(6)
	v_pk_mul_f32 v[76:77], v[20:21], v[0:1]
	ds_read_b128 v[24:27], v17 offset:6912
	v_pk_fma_f32 v[76:77], v[22:23], v[2:3], v[76:77]
	ds_read_b128 v[28:31], v17 offset:15104
	v_add_f32_e32 v76, v76, v77
	ds_read_b32 v18, v19 offset:20832
	ds_read_b128 v[32:35], v17 offset:2816
	v_add_f32_dpp v76, v76, v76 quad_perm:[1,0,3,2] row_mask:0xf bank_mask:0xf bound_ctrl:1
	s_waitcnt lgkmcnt(8)
	v_pk_mul_f32 v[78:79], v[4:5], v[16:17] op_sel_hi:[1,0]
	v_pk_mul_f32 v[80:81], v[6:7], v[16:17] op_sel_hi:[1,0]
	v_add_f32_dpp v76, v76, v76 quad_perm:[2,3,0,1] row_mask:0xf bank_mask:0xf bound_ctrl:1
	s_waitcnt lgkmcnt(6)
	v_pk_mul_f32 v[250:251], v[72:73], v[20:21]
	v_pk_fma_f32 v[78:79], v[20:21], v[8:9], v[78:79]
	v_add_f32_dpp v76, v76, v76 row_half_mirror row_mask:0xf bank_mask:0xf bound_ctrl:1
	v_pk_fma_f32 v[250:251], v[74:75], v[22:23], v[250:251]
	v_pk_fma_f32 v[80:81], v[22:23], v[10:11], v[80:81]
	v_add_f32_dpp v76, v76, v76 row_ror:8 row_mask:0xf bank_mask:0xf bound_ctrl:1
	ds_read_b128 v[68:71], v17 offset:18944
	s_waitcnt lgkmcnt(6)
	v_pk_fma_f32 v[20:21], v[12:13], v[76:77], v[78:79] op_sel_hi:[1,0,1] neg_lo:[1,0,0] neg_hi:[1,0,0]
	v_pk_fma_f32 v[22:23], v[14:15], v[76:77], v[80:81] op_sel_hi:[1,0,1] neg_lo:[1,0,0] neg_hi:[1,0,0]
	v_add_f32_e32 v250, v250, v251
	ds_read_b128 v[36:39], v17 offset:11008
	ds_write_b32 v252, v250 offset:4608
	s_waitcnt lgkmcnt(6)
	v_pk_mul_f32 v[76:77], v[20:21], v[24:25]
	ds_read_b128 v[0:3], v17 offset:7168
	v_pk_fma_f32 v[76:77], v[22:23], v[26:27], v[76:77]
	ds_read_b128 v[4:7], v17 offset:15360
	v_add_f32_e32 v76, v76, v77
	ds_read_b32 v16, v19 offset:20864
	ds_read_b128 v[8:11], v17 offset:3072
	v_add_f32_dpp v76, v76, v76 quad_perm:[1,0,3,2] row_mask:0xf bank_mask:0xf bound_ctrl:1
	s_waitcnt lgkmcnt(8)
	v_pk_mul_f32 v[78:79], v[28:29], v[18:19] op_sel_hi:[1,0]
	v_pk_mul_f32 v[80:81], v[30:31], v[18:19] op_sel_hi:[1,0]
	v_add_f32_dpp v76, v76, v76 quad_perm:[2,3,0,1] row_mask:0xf bank_mask:0xf bound_ctrl:1
	s_waitcnt lgkmcnt(6)
	v_pk_mul_f32 v[250:251], v[68:69], v[20:21]
	v_pk_fma_f32 v[78:79], v[20:21], v[32:33], v[78:79]
	v_add_f32_dpp v76, v76, v76 row_half_mirror row_mask:0xf bank_mask:0xf bound_ctrl:1
	v_pk_fma_f32 v[250:251], v[70:71], v[22:23], v[250:251]
	v_pk_fma_f32 v[80:81], v[22:23], v[34:35], v[80:81]
	v_add_f32_dpp v76, v76, v76 row_ror:8 row_mask:0xf bank_mask:0xf bound_ctrl:1
	ds_read_b128 v[72:75], v17 offset:19200
	s_waitcnt lgkmcnt(6)
	v_pk_fma_f32 v[20:21], v[36:37], v[76:77], v[78:79] op_sel_hi:[1,0,1] neg_lo:[1,0,0] neg_hi:[1,0,0]
	v_pk_fma_f32 v[22:23], v[38:39], v[76:77], v[80:81] op_sel_hi:[1,0,1] neg_lo:[1,0,0] neg_hi:[1,0,0]
	v_add_f32_e32 v250, v250, v251
	ds_read_b128 v[12:15], v17 offset:11264
	ds_write_b32 v252, v250 offset:5120
	s_waitcnt lgkmcnt(6)
	v_pk_mul_f32 v[76:77], v[20:21], v[0:1]
	ds_read_b128 v[24:27], v17 offset:7424
	v_pk_fma_f32 v[76:77], v[22:23], v[2:3], v[76:77]
	ds_read_b128 v[28:31], v17 offset:15616
	v_add_f32_e32 v76, v76, v77
	ds_read_b32 v18, v19 offset:20896
	ds_read_b128 v[32:35], v17 offset:3328
	v_add_f32_dpp v76, v76, v76 quad_perm:[1,0,3,2] row_mask:0xf bank_mask:0xf bound_ctrl:1
	s_waitcnt lgkmcnt(8)
	v_pk_mul_f32 v[78:79], v[4:5], v[16:17] op_sel_hi:[1,0]
	v_pk_mul_f32 v[80:81], v[6:7], v[16:17] op_sel_hi:[1,0]
	v_add_f32_dpp v76, v76, v76 quad_perm:[2,3,0,1] row_mask:0xf bank_mask:0xf bound_ctrl:1
	s_waitcnt lgkmcnt(6)
	v_pk_mul_f32 v[250:251], v[72:73], v[20:21]
	v_pk_fma_f32 v[78:79], v[20:21], v[8:9], v[78:79]
	v_add_f32_dpp v76, v76, v76 row_half_mirror row_mask:0xf bank_mask:0xf bound_ctrl:1
	v_pk_fma_f32 v[250:251], v[74:75], v[22:23], v[250:251]
	v_pk_fma_f32 v[80:81], v[22:23], v[10:11], v[80:81]
	v_add_f32_dpp v76, v76, v76 row_ror:8 row_mask:0xf bank_mask:0xf bound_ctrl:1
	ds_read_b128 v[68:71], v17 offset:19456
	s_waitcnt lgkmcnt(6)
	v_pk_fma_f32 v[20:21], v[12:13], v[76:77], v[78:79] op_sel_hi:[1,0,1] neg_lo:[1,0,0] neg_hi:[1,0,0]
	v_pk_fma_f32 v[22:23], v[14:15], v[76:77], v[80:81] op_sel_hi:[1,0,1] neg_lo:[1,0,0] neg_hi:[1,0,0]
	v_add_f32_e32 v250, v250, v251
	ds_read_b128 v[36:39], v17 offset:11520
	ds_write_b32 v252, v250 offset:5632
	s_waitcnt lgkmcnt(6)
	v_pk_mul_f32 v[76:77], v[20:21], v[24:25]
	ds_read_b128 v[0:3], v17 offset:7680
	v_pk_fma_f32 v[76:77], v[22:23], v[26:27], v[76:77]
	ds_read_b128 v[4:7], v17 offset:15872
	v_add_f32_e32 v76, v76, v77
	ds_read_b32 v16, v19 offset:20928
	ds_read_b128 v[8:11], v17 offset:3584
	v_add_f32_dpp v76, v76, v76 quad_perm:[1,0,3,2] row_mask:0xf bank_mask:0xf bound_ctrl:1
	s_waitcnt lgkmcnt(8)
	v_pk_mul_f32 v[78:79], v[28:29], v[18:19] op_sel_hi:[1,0]
	v_pk_mul_f32 v[80:81], v[30:31], v[18:19] op_sel_hi:[1,0]
	v_add_f32_dpp v76, v76, v76 quad_perm:[2,3,0,1] row_mask:0xf bank_mask:0xf bound_ctrl:1
	s_waitcnt lgkmcnt(6)
	v_pk_mul_f32 v[250:251], v[68:69], v[20:21]
	v_pk_fma_f32 v[78:79], v[20:21], v[32:33], v[78:79]
	v_add_f32_dpp v76, v76, v76 row_half_mirror row_mask:0xf bank_mask:0xf bound_ctrl:1
	v_pk_fma_f32 v[250:251], v[70:71], v[22:23], v[250:251]
	v_pk_fma_f32 v[80:81], v[22:23], v[34:35], v[80:81]
	v_add_f32_dpp v76, v76, v76 row_ror:8 row_mask:0xf bank_mask:0xf bound_ctrl:1
	ds_read_b128 v[72:75], v17 offset:19712
	s_waitcnt lgkmcnt(6)
	v_pk_fma_f32 v[20:21], v[36:37], v[76:77], v[78:79] op_sel_hi:[1,0,1] neg_lo:[1,0,0] neg_hi:[1,0,0]
	v_pk_fma_f32 v[22:23], v[38:39], v[76:77], v[80:81] op_sel_hi:[1,0,1] neg_lo:[1,0,0] neg_hi:[1,0,0]
	v_add_f32_e32 v250, v250, v251
	ds_read_b128 v[12:15], v17 offset:11776
	ds_write_b32 v252, v250 offset:6144
	s_waitcnt lgkmcnt(6)
	v_pk_mul_f32 v[76:77], v[20:21], v[0:1]
	ds_read_b128 v[24:27], v17 offset:7936
	v_pk_fma_f32 v[76:77], v[22:23], v[2:3], v[76:77]
	ds_read_b128 v[28:31], v17 offset:16128
	v_add_f32_e32 v76, v76, v77
	ds_read_b32 v18, v19 offset:20960
	ds_read_b128 v[32:35], v17 offset:3840
	v_add_f32_dpp v76, v76, v76 quad_perm:[1,0,3,2] row_mask:0xf bank_mask:0xf bound_ctrl:1
	s_waitcnt lgkmcnt(8)
	v_pk_mul_f32 v[78:79], v[4:5], v[16:17] op_sel_hi:[1,0]
	v_pk_mul_f32 v[80:81], v[6:7], v[16:17] op_sel_hi:[1,0]
	v_add_f32_dpp v76, v76, v76 quad_perm:[2,3,0,1] row_mask:0xf bank_mask:0xf bound_ctrl:1
	s_waitcnt lgkmcnt(6)
	v_pk_mul_f32 v[250:251], v[72:73], v[20:21]
	v_pk_fma_f32 v[78:79], v[20:21], v[8:9], v[78:79]
	v_add_f32_dpp v76, v76, v76 row_half_mirror row_mask:0xf bank_mask:0xf bound_ctrl:1
	v_pk_fma_f32 v[250:251], v[74:75], v[22:23], v[250:251]
	v_pk_fma_f32 v[80:81], v[22:23], v[10:11], v[80:81]
	v_add_f32_dpp v76, v76, v76 row_ror:8 row_mask:0xf bank_mask:0xf bound_ctrl:1
	ds_read_b128 v[68:71], v17 offset:19968
	s_waitcnt lgkmcnt(6)
	v_pk_fma_f32 v[20:21], v[12:13], v[76:77], v[78:79] op_sel_hi:[1,0,1] neg_lo:[1,0,0] neg_hi:[1,0,0]
	v_pk_fma_f32 v[22:23], v[14:15], v[76:77], v[80:81] op_sel_hi:[1,0,1] neg_lo:[1,0,0] neg_hi:[1,0,0]
	v_add_f32_e32 v250, v250, v251
	ds_read_b128 v[36:39], v17 offset:12032
	ds_write_b32 v252, v250 offset:6656
	s_waitcnt lgkmcnt(6)
	v_pk_mul_f32 v[76:77], v[20:21], v[24:25]
	s_nop 0
	v_pk_fma_f32 v[76:77], v[22:23], v[26:27], v[76:77]
	s_nop 0
	v_add_f32_e32 v76, v76, v77
	s_nop 1
	v_add_f32_dpp v76, v76, v76 quad_perm:[1,0,3,2] row_mask:0xf bank_mask:0xf bound_ctrl:1
	s_waitcnt lgkmcnt(4)
	v_pk_mul_f32 v[78:79], v[28:29], v[18:19] op_sel_hi:[1,0]
	v_pk_mul_f32 v[80:81], v[30:31], v[18:19] op_sel_hi:[1,0]
	v_add_f32_dpp v76, v76, v76 quad_perm:[2,3,0,1] row_mask:0xf bank_mask:0xf bound_ctrl:1
	s_waitcnt lgkmcnt(2)
	v_pk_mul_f32 v[250:251], v[68:69], v[20:21]
	v_pk_fma_f32 v[78:79], v[20:21], v[32:33], v[78:79]
	v_add_f32_dpp v76, v76, v76 row_half_mirror row_mask:0xf bank_mask:0xf bound_ctrl:1
	v_pk_fma_f32 v[250:251], v[70:71], v[22:23], v[250:251]
	v_pk_fma_f32 v[80:81], v[22:23], v[34:35], v[80:81]
	v_add_f32_dpp v76, v76, v76 row_ror:8 row_mask:0xf bank_mask:0xf bound_ctrl:1
	ds_read_b128 v[72:75], v17 offset:20224
	s_waitcnt lgkmcnt(2)
	v_pk_fma_f32 v[20:21], v[36:37], v[76:77], v[78:79] op_sel_hi:[1,0,1] neg_lo:[1,0,0] neg_hi:[1,0,0]
	v_pk_fma_f32 v[22:23], v[38:39], v[76:77], v[80:81] op_sel_hi:[1,0,1] neg_lo:[1,0,0] neg_hi:[1,0,0]
	v_add_f32_e32 v250, v250, v251
	ds_write_b32 v252, v250 offset:7168
	s_waitcnt lgkmcnt(1)
	v_pk_mul_f32 v[250:251], v[72:73], v[20:21]
	s_nop 0
	v_pk_fma_f32 v[250:251], v[74:75], v[22:23], v[250:251]
	s_nop 0
	v_add_f32_e32 v250, v250, v251
	ds_write_b32 v252, v250 offset:7680
	s_waitcnt lgkmcnt(0)
	s_barrier
	s_add_i32 s52, s52, 1
	s_cmpk_eq_i32 s52, 0x200
	s_cbranch_scc0 .Lsc_chunk

	.amdhsa_kernel _Z14fwd_megakernel6Params
		.amdhsa_group_segment_fixed_size 0
		.amdhsa_private_segment_fixed_size 0
		.amdhsa_kernarg_size 616
		.amdhsa_user_sgpr_count 2
		.amdhsa_user_sgpr_dispatch_ptr 0
		.amdhsa_user_sgpr_queue_ptr 0
		.amdhsa_user_sgpr_kernarg_segment_ptr 1
		.amdhsa_user_sgpr_dispatch_id 0
		.amdhsa_user_sgpr_kernarg_preload_length 0
		.amdhsa_user_sgpr_kernarg_preload_offset 0
		.amdhsa_user_sgpr_private_segment_size 0
		.amdhsa_uses_dynamic_stack 0
		.amdhsa_enable_private_segment 0
		.amdhsa_system_sgpr_workgroup_id_x 1
		.amdhsa_system_sgpr_workgroup_id_y 0
		.amdhsa_system_sgpr_workgroup_id_z 0
		.amdhsa_system_sgpr_workgroup_info 0
		.amdhsa_system_vgpr_workitem_id 2
		.amdhsa_next_free_vgpr 256
		.amdhsa_next_free_sgpr 100
		.amdhsa_accum_offset 256
		.amdhsa_reserve_vcc 1
		.amdhsa_float_round_mode_32 0
		.amdhsa_float_round_mode_16_64 0
		.amdhsa_float_denorm_mode_32 3
		.amdhsa_float_denorm_mode_16_64 3
		.amdhsa_dx10_clamp 1
		.amdhsa_ieee_mode 1
		.amdhsa_fp16_overflow 0
		.amdhsa_tg_split 0
		.amdhsa_exception_fp_ieee_invalid_op 0
		.amdhsa_exception_fp_denorm_src 0
		.amdhsa_exception_fp_ieee_div_zero 0
		.amdhsa_exception_fp_ieee_overflow 0
		.amdhsa_exception_fp_ieee_underflow 0
		.amdhsa_exception_fp_ieee_inexact 0
		.amdhsa_exception_int_div_zero 0
	.end_amdhsa_kernel

amdhsa.kernels:
  - .agpr_count:     0
    .args:
      - .offset:         0
        .size:           360
        .value_kind:     by_value
      - .offset:         360
        .size:           4
        .value_kind:     hidden_block_count_x
      - .offset:         364
        .size:           4
        .value_kind:     hidden_block_count_y
      - .offset:         368
        .size:           4
        .value_kind:     hidden_block_count_z
      - .offset:         372
        .size:           2
        .value_kind:     hidden_group_size_x
      - .offset:         374
        .size:           2
        .value_kind:     hidden_group_size_y
      - .offset:         376
        .size:           2
        .value_kind:     hidden_group_size_z
      - .offset:         378
        .size:           2
        .value_kind:     hidden_remainder_x
      - .offset:         380
        .size:           2
        .value_kind:     hidden_remainder_y
      - .offset:         382
        .size:           2
        .value_kind:     hidden_remainder_z
      - .offset:         400
        .size:           8
        .value_kind:     hidden_global_offset_x
      - .offset:         408
        .size:           8
        .value_kind:     hidden_global_offset_y
      - .offset:         416
        .size:           8
        .value_kind:     hidden_global_offset_z
      - .offset:         424
        .size:           2
        .value_kind:     hidden_grid_dims
      - .offset:         448
        .size:           8
        .value_kind:     hidden_multigrid_sync_arg
      - .offset:         480
        .size:           4
        .value_kind:     hidden_dynamic_lds_size
    .group_segment_fixed_size: 0
    .kernarg_segment_align: 8
    .kernarg_segment_size: 616
    .language:       OpenCL C
    .language_version:
      - 2
      - 0
    .max_flat_workgroup_size: 512
    .name:           _Z14fwd_megakernel6Params
    .private_segment_fixed_size: 0
    .sgpr_count:     106
    .sgpr_spill_count: 95
    .symbol:         _Z14fwd_megakernel6Params.kd
    .uniform_work_group_size: 1
    .uses_dynamic_stack: false
    .vgpr_count:     256
    .vgpr_spill_count: 0
    .wavefront_size: 64
